# indexer radix passes: histogram bin of a matching key by v_bfe_u32 + cndmask + lshl_add (3 ops) instead of 5
# baseline (speedup 1.0000x reference)
; #define SEL_HADD(idx_) __hip_atomic_fetch_add(&hist[(idx_)], 1u, __ATOMIC_RELAXED, __HIP_MEMORY_SCOPE_WORKGROUP)
; __device__ __forceinline__ void sel_unit(LAS char* lds, int b, int u, const bf16_t* QI, const bf16_t* KIDX, const float* WIDX, unsigned long long* MASK) {
;     ...
;     for (int pass = 1; pass < 4; ++pass) {
;         const int shift = 24 - 8 * pass;
;         { const int t_ = opaque_tid(); for (int i = t_; i < 4096; i += 512) hist[i] = 0u; }
;         __syncthreads();
;         const unsigned pf = pref[q16];
;         unsigned zz = 0u; asm volatile("" : "+v"(zz));
; #pragma unroll
;         for (int j = 0; j < 8; ++j) if (j < nj) {
; #pragma unroll
;             for (int kb = 0; kb < 4; ++kb)
; #pragma unroll
;                 for (int i = 0; i < 4; ++i) { const unsigned k = sc[j][kb][i] | zz; SEL_HADD((((k >> (shift + 8)) == pf) ? ((k >> shift) & 255u) * 16 : 4096u) + q16); __builtin_amdgcn_sched_barrier(0); }
.LBB0_706:
	ds_read_b32 v2, v60 offset:34880
	s_lshl_b32 s2, s21, 3
	s_sub_i32 s16, 24, s2
	v_mov_b32_e32 v3, 0
	v_mov_b32_e32 v41, 0x100
	s_sub_i32 s17, 32, s2
	s_and_b64 vcc, exec, s[22:23]
	s_cbranch_vccz .LBB0_711
	v_lshrrev_b32_e32 v5, s17, v62
	s_waitcnt lgkmcnt(0)
	v_cmp_eq_u32_e32 vcc, v5, v2
	s_cbranch_vccz .Lsel_skip_1
	v_bfe_u32 v4, v62, s16, 8
	v_cndmask_b32_e32 v4, v41, v4, vcc
	v_lshl_add_u32 v4, v4, 6, v0
	ds_add_u32 v4, v205 offset:16384
.Lsel_skip_1:
	v_lshrrev_b32_e32 v5, s17, v61
	v_cmp_eq_u32_e32 vcc, v5, v2
	s_cbranch_vccz .Lsel_skip_2
	v_bfe_u32 v4, v61, s16, 8
	v_cndmask_b32_e32 v4, v41, v4, vcc
	v_lshl_add_u32 v4, v4, 6, v0
	ds_add_u32 v4, v205 offset:16384
.Lsel_skip_2:
	v_lshrrev_b32_e32 v5, s17, v64
	v_cmp_eq_u32_e32 vcc, v5, v2
	s_cbranch_vccz .Lsel_skip_3
	v_bfe_u32 v4, v64, s16, 8
	v_cndmask_b32_e32 v4, v41, v4, vcc
	v_lshl_add_u32 v4, v4, 6, v0
	ds_add_u32 v4, v205 offset:16384
.Lsel_skip_3:
	v_lshrrev_b32_e32 v5, s17, v63
	v_cmp_eq_u32_e32 vcc, v5, v2
	s_cbranch_vccz .Lsel_skip_4
	v_bfe_u32 v4, v63, s16, 8
	v_cndmask_b32_e32 v4, v41, v4, vcc
	v_lshl_add_u32 v4, v4, 6, v0
	ds_add_u32 v4, v205 offset:16384
.Lsel_skip_4:
	v_lshrrev_b32_e32 v5, s17, v66
	v_cmp_eq_u32_e32 vcc, v5, v2
	s_cbranch_vccz .Lsel_skip_5
	v_bfe_u32 v4, v66, s16, 8
	v_cndmask_b32_e32 v4, v41, v4, vcc
	v_lshl_add_u32 v4, v4, 6, v0
	ds_add_u32 v4, v205 offset:16384
.Lsel_skip_5:
	v_lshrrev_b32_e32 v5, s17, v65
	v_cmp_eq_u32_e32 vcc, v5, v2
	s_cbranch_vccz .Lsel_skip_6
	v_bfe_u32 v4, v65, s16, 8
	v_cndmask_b32_e32 v4, v41, v4, vcc
	v_lshl_add_u32 v4, v4, 6, v0
	ds_add_u32 v4, v205 offset:16384
.Lsel_skip_6:
	v_lshrrev_b32_e32 v5, s17, v68
	v_cmp_eq_u32_e32 vcc, v5, v2
	s_cbranch_vccz .Lsel_skip_7
	v_bfe_u32 v4, v68, s16, 8
	v_cndmask_b32_e32 v4, v41, v4, vcc
	v_lshl_add_u32 v4, v4, 6, v0
	ds_add_u32 v4, v205 offset:16384
.Lsel_skip_7:
	v_lshrrev_b32_e32 v5, s17, v67
	v_cmp_eq_u32_e32 vcc, v5, v2
	s_cbranch_vccz .Lsel_skip_8
	v_bfe_u32 v4, v67, s16, 8
	v_cndmask_b32_e32 v4, v41, v4, vcc
	v_lshl_add_u32 v4, v4, 6, v0
	ds_add_u32 v4, v205 offset:16384
.Lsel_skip_8:
	v_lshrrev_b32_e32 v5, s17, v70
	v_cmp_eq_u32_e32 vcc, v5, v2
	s_cbranch_vccz .Lsel_skip_9
	v_bfe_u32 v4, v70, s16, 8
	v_cndmask_b32_e32 v4, v41, v4, vcc
	v_lshl_add_u32 v4, v4, 6, v0
	ds_add_u32 v4, v205 offset:16384
.Lsel_skip_9:
	v_lshrrev_b32_e32 v5, s17, v69
	v_cmp_eq_u32_e32 vcc, v5, v2
	s_cbranch_vccz .Lsel_skip_10
	v_bfe_u32 v4, v69, s16, 8
	v_cndmask_b32_e32 v4, v41, v4, vcc
	v_lshl_add_u32 v4, v4, 6, v0
	ds_add_u32 v4, v205 offset:16384
.Lsel_skip_10:
	v_lshrrev_b32_e32 v5, s17, v72
	v_cmp_eq_u32_e32 vcc, v5, v2
	s_cbranch_vccz .Lsel_skip_11
	v_bfe_u32 v4, v72, s16, 8
	v_cndmask_b32_e32 v4, v41, v4, vcc
	v_lshl_add_u32 v4, v4, 6, v0
	ds_add_u32 v4, v205 offset:16384
.Lsel_skip_11:
	v_lshrrev_b32_e32 v5, s17, v71
	v_cmp_eq_u32_e32 vcc, v5, v2
	s_cbranch_vccz .Lsel_skip_12
	v_bfe_u32 v4, v71, s16, 8
	v_cndmask_b32_e32 v4, v41, v4, vcc
	v_lshl_add_u32 v4, v4, 6, v0
	ds_add_u32 v4, v205 offset:16384
.Lsel_skip_12:
	v_lshrrev_b32_e32 v5, s17, v74
	v_cmp_eq_u32_e32 vcc, v5, v2
	s_cbranch_vccz .Lsel_skip_13
	v_bfe_u32 v4, v74, s16, 8
	v_cndmask_b32_e32 v4, v41, v4, vcc
	v_lshl_add_u32 v4, v4, 6, v0
	ds_add_u32 v4, v205 offset:16384
.Lsel_skip_13:
	v_lshrrev_b32_e32 v5, s17, v73
	v_cmp_eq_u32_e32 vcc, v5, v2
	s_cbranch_vccz .Lsel_skip_14
	v_bfe_u32 v4, v73, s16, 8
	v_cndmask_b32_e32 v4, v41, v4, vcc
	v_lshl_add_u32 v4, v4, 6, v0
	ds_add_u32 v4, v205 offset:16384
.Lsel_skip_14:
	v_lshrrev_b32_e32 v5, s17, v76
	v_cmp_eq_u32_e32 vcc, v5, v2
	s_cbranch_vccz .Lsel_skip_15
	v_bfe_u32 v4, v76, s16, 8
	v_cndmask_b32_e32 v4, v41, v4, vcc
	v_lshl_add_u32 v4, v4, 6, v0
	ds_add_u32 v4, v205 offset:16384
.Lsel_skip_15:
	v_lshrrev_b32_e32 v5, s17, v75
	v_cmp_eq_u32_e32 vcc, v5, v2
	s_cbranch_vccz .Lsel_skip_16
	v_bfe_u32 v4, v75, s16, 8
	v_cndmask_b32_e32 v4, v41, v4, vcc
	v_lshl_add_u32 v4, v4, 6, v0
	ds_add_u32 v4, v205 offset:16384
; #define SEL_HADD(idx_) __hip_atomic_fetch_add(&hist[(idx_)], 1u, __ATOMIC_RELAXED, __HIP_MEMORY_SCOPE_WORKGROUP)
; __device__ __forceinline__ void sel_unit(LAS char* lds, int b, int u, const bf16_t* QI, const bf16_t* KIDX, const float* WIDX, unsigned long long* MASK) {
;     ...
;         for (int j = 0; j < 8; ++j) if (j < nj) {
; #pragma unroll
;             for (int kb = 0; kb < 4; ++kb)
; #pragma unroll
;                 for (int i = 0; i < 4; ++i) { const unsigned k = sc[j][kb][i] | zz; SEL_HADD((((k >> (shift + 8)) == pf) ? ((k >> shift) & 255u) * 16 : 4096u) + q16); __builtin_amdgcn_sched_barrier(0); }
.Lsel_skip_16:
.LBB0_711:
	v_cndmask_b32_e64 v4, 0, 1, s[18:19]
	v_cmp_ne_u32_e64 s[2:3], 1, v4
	s_andn2_b64 vcc, exec, s[18:19]
	s_cbranch_vccnz .LBB0_741
	v_lshrrev_b32_e32 v5, s17, v78
	s_waitcnt lgkmcnt(0)
	v_cmp_eq_u32_e32 vcc, v5, v2
	s_cbranch_vccz .Lsel_skip_17
	v_bfe_u32 v4, v78, s16, 8
	v_cndmask_b32_e32 v4, v41, v4, vcc
	v_lshl_add_u32 v4, v4, 6, v0
	ds_add_u32 v4, v205 offset:16384
.Lsel_skip_17:
	v_lshrrev_b32_e32 v5, s17, v77
	v_cmp_eq_u32_e32 vcc, v5, v2
	s_cbranch_vccz .Lsel_skip_18
	v_bfe_u32 v4, v77, s16, 8
	v_cndmask_b32_e32 v4, v41, v4, vcc
	v_lshl_add_u32 v4, v4, 6, v0
	ds_add_u32 v4, v205 offset:16384
.Lsel_skip_18:
	v_lshrrev_b32_e32 v5, s17, v80
	v_cmp_eq_u32_e32 vcc, v5, v2
	s_cbranch_vccz .Lsel_skip_19
	v_bfe_u32 v4, v80, s16, 8
	v_cndmask_b32_e32 v4, v41, v4, vcc
	v_lshl_add_u32 v4, v4, 6, v0
	ds_add_u32 v4, v205 offset:16384
.Lsel_skip_19:
	v_lshrrev_b32_e32 v5, s17, v79
	v_cmp_eq_u32_e32 vcc, v5, v2
	s_cbranch_vccz .Lsel_skip_20
	v_bfe_u32 v4, v79, s16, 8
	v_cndmask_b32_e32 v4, v41, v4, vcc
	v_lshl_add_u32 v4, v4, 6, v0
	ds_add_u32 v4, v205 offset:16384
.Lsel_skip_20:
	v_lshrrev_b32_e32 v5, s17, v82
	v_cmp_eq_u32_e32 vcc, v5, v2
	s_cbranch_vccz .Lsel_skip_21
	v_bfe_u32 v4, v82, s16, 8
	v_cndmask_b32_e32 v4, v41, v4, vcc
	v_lshl_add_u32 v4, v4, 6, v0
	ds_add_u32 v4, v205 offset:16384
.Lsel_skip_21:
	v_lshrrev_b32_e32 v5, s17, v81
	v_cmp_eq_u32_e32 vcc, v5, v2
	s_cbranch_vccz .Lsel_skip_22
	v_bfe_u32 v4, v81, s16, 8
	v_cndmask_b32_e32 v4, v41, v4, vcc
	v_lshl_add_u32 v4, v4, 6, v0
	ds_add_u32 v4, v205 offset:16384
.Lsel_skip_22:
	v_lshrrev_b32_e32 v5, s17, v84
	v_cmp_eq_u32_e32 vcc, v5, v2
	s_cbranch_vccz .Lsel_skip_23
	v_bfe_u32 v4, v84, s16, 8
	v_cndmask_b32_e32 v4, v41, v4, vcc
	v_lshl_add_u32 v4, v4, 6, v0
	ds_add_u32 v4, v205 offset:16384
.Lsel_skip_23:
	v_lshrrev_b32_e32 v5, s17, v83
	v_cmp_eq_u32_e32 vcc, v5, v2
	s_cbranch_vccz .Lsel_skip_24
	v_bfe_u32 v4, v83, s16, 8
	v_cndmask_b32_e32 v4, v41, v4, vcc
	v_lshl_add_u32 v4, v4, 6, v0
	ds_add_u32 v4, v205 offset:16384
.Lsel_skip_24:
	v_lshrrev_b32_e32 v5, s17, v86
	v_cmp_eq_u32_e32 vcc, v5, v2
	s_cbranch_vccz .Lsel_skip_25
	v_bfe_u32 v4, v86, s16, 8
	v_cndmask_b32_e32 v4, v41, v4, vcc
	v_lshl_add_u32 v4, v4, 6, v0
	ds_add_u32 v4, v205 offset:16384
.Lsel_skip_25:
	v_lshrrev_b32_e32 v5, s17, v85
	v_cmp_eq_u32_e32 vcc, v5, v2
	s_cbranch_vccz .Lsel_skip_26
	v_bfe_u32 v4, v85, s16, 8
	v_cndmask_b32_e32 v4, v41, v4, vcc
	v_lshl_add_u32 v4, v4, 6, v0
	ds_add_u32 v4, v205 offset:16384
.Lsel_skip_26:
	v_lshrrev_b32_e32 v5, s17, v88
	v_cmp_eq_u32_e32 vcc, v5, v2
	s_cbranch_vccz .Lsel_skip_27
	v_bfe_u32 v4, v88, s16, 8
	v_cndmask_b32_e32 v4, v41, v4, vcc
	v_lshl_add_u32 v4, v4, 6, v0
	ds_add_u32 v4, v205 offset:16384
.Lsel_skip_27:
	v_lshrrev_b32_e32 v5, s17, v87
	v_cmp_eq_u32_e32 vcc, v5, v2
	s_cbranch_vccz .Lsel_skip_28
	v_bfe_u32 v4, v87, s16, 8
	v_cndmask_b32_e32 v4, v41, v4, vcc
	v_lshl_add_u32 v4, v4, 6, v0
	ds_add_u32 v4, v205 offset:16384
.Lsel_skip_28:
	v_lshrrev_b32_e32 v5, s17, v90
	v_cmp_eq_u32_e32 vcc, v5, v2
	s_cbranch_vccz .Lsel_skip_29
	v_bfe_u32 v4, v90, s16, 8
	v_cndmask_b32_e32 v4, v41, v4, vcc
	v_lshl_add_u32 v4, v4, 6, v0
	ds_add_u32 v4, v205 offset:16384
.Lsel_skip_29:
	v_lshrrev_b32_e32 v5, s17, v89
	v_cmp_eq_u32_e32 vcc, v5, v2
	s_cbranch_vccz .Lsel_skip_30
	v_bfe_u32 v4, v89, s16, 8
	v_cndmask_b32_e32 v4, v41, v4, vcc
	v_lshl_add_u32 v4, v4, 6, v0
	ds_add_u32 v4, v205 offset:16384
.Lsel_skip_30:
	v_lshrrev_b32_e32 v5, s17, v92
	v_cmp_eq_u32_e32 vcc, v5, v2
	s_cbranch_vccz .Lsel_skip_31
	v_bfe_u32 v4, v92, s16, 8
	v_cndmask_b32_e32 v4, v41, v4, vcc
	v_lshl_add_u32 v4, v4, 6, v0
	ds_add_u32 v4, v205 offset:16384
.Lsel_skip_31:
	v_lshrrev_b32_e32 v5, s17, v91
	v_cmp_eq_u32_e32 vcc, v5, v2
	s_cbranch_vccz .Lsel_skip_32
	v_bfe_u32 v4, v91, s16, 8
	v_cndmask_b32_e32 v4, v41, v4, vcc
	v_lshl_add_u32 v4, v4, 6, v0
	ds_add_u32 v4, v205 offset:16384

; #define SEL_HADD(idx_) __hip_atomic_fetch_add(&hist[(idx_)], 1u, __ATOMIC_RELAXED, __HIP_MEMORY_SCOPE_WORKGROUP)
; __device__ __forceinline__ void sel_unit(LAS char* lds, int b, int u, const bf16_t* QI, const bf16_t* KIDX, const float* WIDX, unsigned long long* MASK) {
;     ...
;         for (int j = 0; j < 8; ++j) if (j < nj) {
; #pragma unroll
;             for (int kb = 0; kb < 4; ++kb)
; #pragma unroll
;                 for (int i = 0; i < 4; ++i) { const unsigned k = sc[j][kb][i] | zz; SEL_HADD((((k >> (shift + 8)) == pf) ? ((k >> shift) & 255u) * 16 : 4096u) + q16); __builtin_amdgcn_sched_barrier(0); }
.LBB0_714:
	v_lshrrev_b32_e32 v5, s17, v110
	s_waitcnt lgkmcnt(0)
	v_cmp_eq_u32_e32 vcc, v5, v2
	s_cbranch_vccz .Lsel_skip_33
	v_bfe_u32 v4, v110, s16, 8
	v_cndmask_b32_e32 v4, v41, v4, vcc
	v_lshl_add_u32 v4, v4, 6, v0
	ds_add_u32 v4, v205 offset:16384
.Lsel_skip_33:
	v_lshrrev_b32_e32 v5, s17, v109
	v_cmp_eq_u32_e32 vcc, v5, v2
	s_cbranch_vccz .Lsel_skip_34
	v_bfe_u32 v4, v109, s16, 8
	v_cndmask_b32_e32 v4, v41, v4, vcc
	v_lshl_add_u32 v4, v4, 6, v0
	ds_add_u32 v4, v205 offset:16384
.Lsel_skip_34:
	v_lshrrev_b32_e32 v5, s17, v112
	v_cmp_eq_u32_e32 vcc, v5, v2
	s_cbranch_vccz .Lsel_skip_35
	v_bfe_u32 v4, v112, s16, 8
	v_cndmask_b32_e32 v4, v41, v4, vcc
	v_lshl_add_u32 v4, v4, 6, v0
	ds_add_u32 v4, v205 offset:16384
.Lsel_skip_35:
	v_lshrrev_b32_e32 v5, s17, v111
	v_cmp_eq_u32_e32 vcc, v5, v2
	s_cbranch_vccz .Lsel_skip_36
	v_bfe_u32 v4, v111, s16, 8
	v_cndmask_b32_e32 v4, v41, v4, vcc
	v_lshl_add_u32 v4, v4, 6, v0
	ds_add_u32 v4, v205 offset:16384
.Lsel_skip_36:
	v_lshrrev_b32_e32 v5, s17, v114
	v_cmp_eq_u32_e32 vcc, v5, v2
	s_cbranch_vccz .Lsel_skip_37
	v_bfe_u32 v4, v114, s16, 8
	v_cndmask_b32_e32 v4, v41, v4, vcc
	v_lshl_add_u32 v4, v4, 6, v0
	ds_add_u32 v4, v205 offset:16384
.Lsel_skip_37:
	v_lshrrev_b32_e32 v5, s17, v113
	v_cmp_eq_u32_e32 vcc, v5, v2
	s_cbranch_vccz .Lsel_skip_38
	v_bfe_u32 v4, v113, s16, 8
	v_cndmask_b32_e32 v4, v41, v4, vcc
	v_lshl_add_u32 v4, v4, 6, v0
	ds_add_u32 v4, v205 offset:16384
.Lsel_skip_38:
	v_lshrrev_b32_e32 v5, s17, v116
	v_cmp_eq_u32_e32 vcc, v5, v2
	s_cbranch_vccz .Lsel_skip_39
	v_bfe_u32 v4, v116, s16, 8
	v_cndmask_b32_e32 v4, v41, v4, vcc
	v_lshl_add_u32 v4, v4, 6, v0
	ds_add_u32 v4, v205 offset:16384
.Lsel_skip_39:
	v_lshrrev_b32_e32 v5, s17, v115
	v_cmp_eq_u32_e32 vcc, v5, v2
	s_cbranch_vccz .Lsel_skip_40
	v_bfe_u32 v4, v115, s16, 8
	v_cndmask_b32_e32 v4, v41, v4, vcc
	v_lshl_add_u32 v4, v4, 6, v0
	ds_add_u32 v4, v205 offset:16384
.Lsel_skip_40:
	v_lshrrev_b32_e32 v5, s17, v118
	v_cmp_eq_u32_e32 vcc, v5, v2
	s_cbranch_vccz .Lsel_skip_41
	v_bfe_u32 v4, v118, s16, 8
	v_cndmask_b32_e32 v4, v41, v4, vcc
	v_lshl_add_u32 v4, v4, 6, v0
	ds_add_u32 v4, v205 offset:16384
.Lsel_skip_41:
	v_lshrrev_b32_e32 v5, s17, v117
	v_cmp_eq_u32_e32 vcc, v5, v2
	s_cbranch_vccz .Lsel_skip_42
	v_bfe_u32 v4, v117, s16, 8
	v_cndmask_b32_e32 v4, v41, v4, vcc
	v_lshl_add_u32 v4, v4, 6, v0
	ds_add_u32 v4, v205 offset:16384
.Lsel_skip_42:
	v_lshrrev_b32_e32 v5, s17, v120
	v_cmp_eq_u32_e32 vcc, v5, v2
	s_cbranch_vccz .Lsel_skip_43
	v_bfe_u32 v4, v120, s16, 8
	v_cndmask_b32_e32 v4, v41, v4, vcc
	v_lshl_add_u32 v4, v4, 6, v0
	ds_add_u32 v4, v205 offset:16384
.Lsel_skip_43:
	v_lshrrev_b32_e32 v5, s17, v119
	v_cmp_eq_u32_e32 vcc, v5, v2
	s_cbranch_vccz .Lsel_skip_44
	v_bfe_u32 v4, v119, s16, 8
	v_cndmask_b32_e32 v4, v41, v4, vcc
	v_lshl_add_u32 v4, v4, 6, v0
	ds_add_u32 v4, v205 offset:16384
.Lsel_skip_44:
	v_lshrrev_b32_e32 v5, s17, v122
	v_cmp_eq_u32_e32 vcc, v5, v2
	s_cbranch_vccz .Lsel_skip_45
	v_bfe_u32 v4, v122, s16, 8
	v_cndmask_b32_e32 v4, v41, v4, vcc
	v_lshl_add_u32 v4, v4, 6, v0
	ds_add_u32 v4, v205 offset:16384
.Lsel_skip_45:
	v_lshrrev_b32_e32 v5, s17, v121
	v_cmp_eq_u32_e32 vcc, v5, v2
	s_cbranch_vccz .Lsel_skip_46
	v_bfe_u32 v4, v121, s16, 8
	v_cndmask_b32_e32 v4, v41, v4, vcc
	v_lshl_add_u32 v4, v4, 6, v0
	ds_add_u32 v4, v205 offset:16384
.Lsel_skip_46:
	v_lshrrev_b32_e32 v5, s17, v124
	v_cmp_eq_u32_e32 vcc, v5, v2
	s_cbranch_vccz .Lsel_skip_47
	v_bfe_u32 v4, v124, s16, 8
	v_cndmask_b32_e32 v4, v41, v4, vcc
	v_lshl_add_u32 v4, v4, 6, v0
	ds_add_u32 v4, v205 offset:16384
.Lsel_skip_47:
	v_lshrrev_b32_e32 v5, s17, v123
	v_cmp_eq_u32_e32 vcc, v5, v2
	s_cbranch_vccz .Lsel_skip_48
	v_bfe_u32 v4, v123, s16, 8
	v_cndmask_b32_e32 v4, v41, v4, vcc
	v_lshl_add_u32 v4, v4, 6, v0
	ds_add_u32 v4, v205 offset:16384

; #define SEL_HADD(idx_) __hip_atomic_fetch_add(&hist[(idx_)], 1u, __ATOMIC_RELAXED, __HIP_MEMORY_SCOPE_WORKGROUP)
; __device__ __forceinline__ void sel_unit(LAS char* lds, int b, int u, const bf16_t* QI, const bf16_t* KIDX, const float* WIDX, unsigned long long* MASK) {
;     ...
;         for (int j = 0; j < 8; ++j) if (j < nj) {
; #pragma unroll
;             for (int kb = 0; kb < 4; ++kb)
; #pragma unroll
;                 for (int i = 0; i < 4; ++i) { const unsigned k = sc[j][kb][i] | zz; SEL_HADD((((k >> (shift + 8)) == pf) ? ((k >> shift) & 255u) * 16 : 4096u) + q16); __builtin_amdgcn_sched_barrier(0); }
.LBB0_716:
	v_lshrrev_b32_e32 v5, s17, v143
	s_waitcnt lgkmcnt(0)
	v_cmp_eq_u32_e32 vcc, v5, v2
	s_cbranch_vccz .Lsel_skip_49
	v_bfe_u32 v4, v143, s16, 8
	v_cndmask_b32_e32 v4, v41, v4, vcc
	v_lshl_add_u32 v4, v4, 6, v0
	ds_add_u32 v4, v205 offset:16384
.Lsel_skip_49:
	v_lshrrev_b32_e32 v5, s17, v142
	v_cmp_eq_u32_e32 vcc, v5, v2
	s_cbranch_vccz .Lsel_skip_50
	v_bfe_u32 v4, v142, s16, 8
	v_cndmask_b32_e32 v4, v41, v4, vcc
	v_lshl_add_u32 v4, v4, 6, v0
	ds_add_u32 v4, v205 offset:16384
.Lsel_skip_50:
	v_lshrrev_b32_e32 v5, s17, v145
	v_cmp_eq_u32_e32 vcc, v5, v2
	s_cbranch_vccz .Lsel_skip_51
	v_bfe_u32 v4, v145, s16, 8
	v_cndmask_b32_e32 v4, v41, v4, vcc
	v_lshl_add_u32 v4, v4, 6, v0
	ds_add_u32 v4, v205 offset:16384
.Lsel_skip_51:
	v_lshrrev_b32_e32 v5, s17, v144
	v_cmp_eq_u32_e32 vcc, v5, v2
	s_cbranch_vccz .Lsel_skip_52
	v_bfe_u32 v4, v144, s16, 8
	v_cndmask_b32_e32 v4, v41, v4, vcc
	v_lshl_add_u32 v4, v4, 6, v0
	ds_add_u32 v4, v205 offset:16384
.Lsel_skip_52:
	v_lshrrev_b32_e32 v5, s17, v147
	v_cmp_eq_u32_e32 vcc, v5, v2
	s_cbranch_vccz .Lsel_skip_53
	v_bfe_u32 v4, v147, s16, 8
	v_cndmask_b32_e32 v4, v41, v4, vcc
	v_lshl_add_u32 v4, v4, 6, v0
	ds_add_u32 v4, v205 offset:16384
.Lsel_skip_53:
	v_lshrrev_b32_e32 v5, s17, v146
	v_cmp_eq_u32_e32 vcc, v5, v2
	s_cbranch_vccz .Lsel_skip_54
	v_bfe_u32 v4, v146, s16, 8
	v_cndmask_b32_e32 v4, v41, v4, vcc
	v_lshl_add_u32 v4, v4, 6, v0
	ds_add_u32 v4, v205 offset:16384
.Lsel_skip_54:
	v_lshrrev_b32_e32 v5, s17, v149
	v_cmp_eq_u32_e32 vcc, v5, v2
	s_cbranch_vccz .Lsel_skip_55
	v_bfe_u32 v4, v149, s16, 8
	v_cndmask_b32_e32 v4, v41, v4, vcc
	v_lshl_add_u32 v4, v4, 6, v0
	ds_add_u32 v4, v205 offset:16384
.Lsel_skip_55:
	v_lshrrev_b32_e32 v5, s17, v148
	v_cmp_eq_u32_e32 vcc, v5, v2
	s_cbranch_vccz .Lsel_skip_56
	v_bfe_u32 v4, v148, s16, 8
	v_cndmask_b32_e32 v4, v41, v4, vcc
	v_lshl_add_u32 v4, v4, 6, v0
	ds_add_u32 v4, v205 offset:16384
.Lsel_skip_56:
	v_lshrrev_b32_e32 v5, s17, v178
	v_cmp_eq_u32_e32 vcc, v5, v2
	s_cbranch_vccz .Lsel_skip_57
	v_bfe_u32 v4, v178, s16, 8
	v_cndmask_b32_e32 v4, v41, v4, vcc
	v_lshl_add_u32 v4, v4, 6, v0
	ds_add_u32 v4, v205 offset:16384
.Lsel_skip_57:
	v_lshrrev_b32_e32 v5, s17, v177
	v_cmp_eq_u32_e32 vcc, v5, v2
	s_cbranch_vccz .Lsel_skip_58
	v_bfe_u32 v4, v177, s16, 8
	v_cndmask_b32_e32 v4, v41, v4, vcc
	v_lshl_add_u32 v4, v4, 6, v0
	ds_add_u32 v4, v205 offset:16384
.Lsel_skip_58:
	v_lshrrev_b32_e32 v5, s17, v186
	v_cmp_eq_u32_e32 vcc, v5, v2
	s_cbranch_vccz .Lsel_skip_59
	v_bfe_u32 v4, v186, s16, 8
	v_cndmask_b32_e32 v4, v41, v4, vcc
	v_lshl_add_u32 v4, v4, 6, v0
	ds_add_u32 v4, v205 offset:16384
.Lsel_skip_59:
	v_lshrrev_b32_e32 v5, s17, v181
	v_cmp_eq_u32_e32 vcc, v5, v2
	s_cbranch_vccz .Lsel_skip_60
	v_bfe_u32 v4, v181, s16, 8
	v_cndmask_b32_e32 v4, v41, v4, vcc
	v_lshl_add_u32 v4, v4, 6, v0
	ds_add_u32 v4, v205 offset:16384
.Lsel_skip_60:
	v_lshrrev_b32_e32 v5, s17, v188
	v_cmp_eq_u32_e32 vcc, v5, v2
	s_cbranch_vccz .Lsel_skip_61
	v_bfe_u32 v4, v188, s16, 8
	v_cndmask_b32_e32 v4, v41, v4, vcc
	v_lshl_add_u32 v4, v4, 6, v0
	ds_add_u32 v4, v205 offset:16384
.Lsel_skip_61:
	v_lshrrev_b32_e32 v5, s17, v187
	v_cmp_eq_u32_e32 vcc, v5, v2
	s_cbranch_vccz .Lsel_skip_62
	v_bfe_u32 v4, v187, s16, 8
	v_cndmask_b32_e32 v4, v41, v4, vcc
	v_lshl_add_u32 v4, v4, 6, v0
	ds_add_u32 v4, v205 offset:16384
.Lsel_skip_62:
	v_lshrrev_b32_e32 v5, s17, v190
	v_cmp_eq_u32_e32 vcc, v5, v2
	s_cbranch_vccz .Lsel_skip_63
	v_bfe_u32 v4, v190, s16, 8
	v_cndmask_b32_e32 v4, v41, v4, vcc
	v_lshl_add_u32 v4, v4, 6, v0
	ds_add_u32 v4, v205 offset:16384
.Lsel_skip_63:
	v_lshrrev_b32_e32 v5, s17, v189
	v_cmp_eq_u32_e32 vcc, v5, v2
	s_cbranch_vccz .Lsel_skip_64
	v_bfe_u32 v4, v189, s16, 8
	v_cndmask_b32_e32 v4, v41, v4, vcc
	v_lshl_add_u32 v4, v4, 6, v0
	ds_add_u32 v4, v205 offset:16384

; #define SEL_HADD(idx_) __hip_atomic_fetch_add(&hist[(idx_)], 1u, __ATOMIC_RELAXED, __HIP_MEMORY_SCOPE_WORKGROUP)
; __device__ __forceinline__ void sel_unit(LAS char* lds, int b, int u, const bf16_t* QI, const bf16_t* KIDX, const float* WIDX, unsigned long long* MASK) {
;     ...
;         for (int j = 0; j < 8; ++j) if (j < nj) {
; #pragma unroll
;             for (int kb = 0; kb < 4; ++kb)
; #pragma unroll
;                 for (int i = 0; i < 4; ++i) { const unsigned k = sc[j][kb][i] | zz; SEL_HADD((((k >> (shift + 8)) == pf) ? ((k >> shift) & 255u) * 16 : 4096u) + q16); __builtin_amdgcn_sched_barrier(0); }
.LBB0_718:
	v_lshrrev_b32_e32 v5, s17, v222
	s_waitcnt lgkmcnt(0)
	v_cmp_eq_u32_e32 vcc, v5, v2
	s_cbranch_vccz .Lsel_skip_65
	v_bfe_u32 v4, v222, s16, 8
	v_cndmask_b32_e32 v4, v41, v4, vcc
	v_lshl_add_u32 v4, v4, 6, v0
	ds_add_u32 v4, v205 offset:16384
.Lsel_skip_65:
	v_lshrrev_b32_e32 v5, s17, v221
	v_cmp_eq_u32_e32 vcc, v5, v2
	s_cbranch_vccz .Lsel_skip_66
	v_bfe_u32 v4, v221, s16, 8
	v_cndmask_b32_e32 v4, v41, v4, vcc
	v_lshl_add_u32 v4, v4, 6, v0
	ds_add_u32 v4, v205 offset:16384
.Lsel_skip_66:
	v_lshrrev_b32_e32 v5, s17, v224
	v_cmp_eq_u32_e32 vcc, v5, v2
	s_cbranch_vccz .Lsel_skip_67
	v_bfe_u32 v4, v224, s16, 8
	v_cndmask_b32_e32 v4, v41, v4, vcc
	v_lshl_add_u32 v4, v4, 6, v0
	ds_add_u32 v4, v205 offset:16384
.Lsel_skip_67:
	v_lshrrev_b32_e32 v5, s17, v223
	v_cmp_eq_u32_e32 vcc, v5, v2
	s_cbranch_vccz .Lsel_skip_68
	v_bfe_u32 v4, v223, s16, 8
	v_cndmask_b32_e32 v4, v41, v4, vcc
	v_lshl_add_u32 v4, v4, 6, v0
	ds_add_u32 v4, v205 offset:16384
.Lsel_skip_68:
	v_lshrrev_b32_e32 v5, s17, v226
	v_cmp_eq_u32_e32 vcc, v5, v2
	s_cbranch_vccz .Lsel_skip_69
	v_bfe_u32 v4, v226, s16, 8
	v_cndmask_b32_e32 v4, v41, v4, vcc
	v_lshl_add_u32 v4, v4, 6, v0
	ds_add_u32 v4, v205 offset:16384
.Lsel_skip_69:
	v_lshrrev_b32_e32 v5, s17, v225
	v_cmp_eq_u32_e32 vcc, v5, v2
	s_cbranch_vccz .Lsel_skip_70
	v_bfe_u32 v4, v225, s16, 8
	v_cndmask_b32_e32 v4, v41, v4, vcc
	v_lshl_add_u32 v4, v4, 6, v0
	ds_add_u32 v4, v205 offset:16384
.Lsel_skip_70:
	v_lshrrev_b32_e32 v5, s17, v228
	v_cmp_eq_u32_e32 vcc, v5, v2
	s_cbranch_vccz .Lsel_skip_71
	v_bfe_u32 v4, v228, s16, 8
	v_cndmask_b32_e32 v4, v41, v4, vcc
	v_lshl_add_u32 v4, v4, 6, v0
	ds_add_u32 v4, v205 offset:16384
.Lsel_skip_71:
	v_lshrrev_b32_e32 v5, s17, v227
	v_cmp_eq_u32_e32 vcc, v5, v2
	s_cbranch_vccz .Lsel_skip_72
	v_bfe_u32 v4, v227, s16, 8
	v_cndmask_b32_e32 v4, v41, v4, vcc
	v_lshl_add_u32 v4, v4, 6, v0
	ds_add_u32 v4, v205 offset:16384
.Lsel_skip_72:
	v_lshrrev_b32_e32 v5, s17, v11
	v_cmp_eq_u32_e32 vcc, v5, v2
	s_cbranch_vccz .Lsel_skip_73
	v_bfe_u32 v4, v11, s16, 8
	v_cndmask_b32_e32 v4, v41, v4, vcc
	v_lshl_add_u32 v4, v4, 6, v0
	ds_add_u32 v4, v205 offset:16384
.Lsel_skip_73:
	v_lshrrev_b32_e32 v5, s17, v10
	v_cmp_eq_u32_e32 vcc, v5, v2
	s_cbranch_vccz .Lsel_skip_74
	v_bfe_u32 v4, v10, s16, 8
	v_cndmask_b32_e32 v4, v41, v4, vcc
	v_lshl_add_u32 v4, v4, 6, v0
	ds_add_u32 v4, v205 offset:16384
.Lsel_skip_74:
	v_lshrrev_b32_e32 v5, s17, v13
	v_cmp_eq_u32_e32 vcc, v5, v2
	s_cbranch_vccz .Lsel_skip_75
	v_bfe_u32 v4, v13, s16, 8
	v_cndmask_b32_e32 v4, v41, v4, vcc
	v_lshl_add_u32 v4, v4, 6, v0
	ds_add_u32 v4, v205 offset:16384
.Lsel_skip_75:
	v_lshrrev_b32_e32 v5, s17, v12
	v_cmp_eq_u32_e32 vcc, v5, v2
	s_cbranch_vccz .Lsel_skip_76
	v_bfe_u32 v4, v12, s16, 8
	v_cndmask_b32_e32 v4, v41, v4, vcc
	v_lshl_add_u32 v4, v4, 6, v0
	ds_add_u32 v4, v205 offset:16384
.Lsel_skip_76:
	v_lshrrev_b32_e32 v5, s17, v15
	v_cmp_eq_u32_e32 vcc, v5, v2
	s_cbranch_vccz .Lsel_skip_77
	v_bfe_u32 v4, v15, s16, 8
	v_cndmask_b32_e32 v4, v41, v4, vcc
	v_lshl_add_u32 v4, v4, 6, v0
	ds_add_u32 v4, v205 offset:16384
.Lsel_skip_77:
	v_lshrrev_b32_e32 v5, s17, v14
	v_cmp_eq_u32_e32 vcc, v5, v2
	s_cbranch_vccz .Lsel_skip_78
	v_bfe_u32 v4, v14, s16, 8
	v_cndmask_b32_e32 v4, v41, v4, vcc
	v_lshl_add_u32 v4, v4, 6, v0
	ds_add_u32 v4, v205 offset:16384
.Lsel_skip_78:
	v_lshrrev_b32_e32 v5, s17, v17
	v_cmp_eq_u32_e32 vcc, v5, v2
	s_cbranch_vccz .Lsel_skip_79
	v_bfe_u32 v4, v17, s16, 8
	v_cndmask_b32_e32 v4, v41, v4, vcc
	v_lshl_add_u32 v4, v4, 6, v0
	ds_add_u32 v4, v205 offset:16384

; #define SEL_HADD(idx_) __hip_atomic_fetch_add(&hist[(idx_)], 1u, __ATOMIC_RELAXED, __HIP_MEMORY_SCOPE_WORKGROUP)
; __device__ __forceinline__ void sel_unit(LAS char* lds, int b, int u, const bf16_t* QI, const bf16_t* KIDX, const float* WIDX, unsigned long long* MASK) {
;     ...
;         for (int j = 0; j < 8; ++j) if (j < nj) {
; #pragma unroll
;             for (int kb = 0; kb < 4; ++kb)
; #pragma unroll
;                 for (int i = 0; i < 4; ++i) { const unsigned k = sc[j][kb][i] | zz; SEL_HADD((((k >> (shift + 8)) == pf) ? ((k >> shift) & 255u) * 16 : 4096u) + q16); __builtin_amdgcn_sched_barrier(0); }
.LBB0_742:
	v_lshrrev_b32_e32 v5, s17, v94
	s_waitcnt lgkmcnt(0)
	v_cmp_eq_u32_e32 vcc, v5, v2
	s_cbranch_vccz .Lsel_skip_80
	v_bfe_u32 v4, v94, s16, 8
	v_cndmask_b32_e32 v4, v41, v4, vcc
	v_lshl_add_u32 v4, v4, 6, v0
	ds_add_u32 v4, v205 offset:16384
.Lsel_skip_80:
	v_lshrrev_b32_e32 v5, s17, v93
	v_cmp_eq_u32_e32 vcc, v5, v2
	s_cbranch_vccz .Lsel_skip_81
	v_bfe_u32 v4, v93, s16, 8
	v_cndmask_b32_e32 v4, v41, v4, vcc
	v_lshl_add_u32 v4, v4, 6, v0
	ds_add_u32 v4, v205 offset:16384
.Lsel_skip_81:
	v_lshrrev_b32_e32 v5, s17, v96
	v_cmp_eq_u32_e32 vcc, v5, v2
	s_cbranch_vccz .Lsel_skip_82
	v_bfe_u32 v4, v96, s16, 8
	v_cndmask_b32_e32 v4, v41, v4, vcc
	v_lshl_add_u32 v4, v4, 6, v0
	ds_add_u32 v4, v205 offset:16384
.Lsel_skip_82:
	v_lshrrev_b32_e32 v5, s17, v95
	v_cmp_eq_u32_e32 vcc, v5, v2
	s_cbranch_vccz .Lsel_skip_83
	v_bfe_u32 v4, v95, s16, 8
	v_cndmask_b32_e32 v4, v41, v4, vcc
	v_lshl_add_u32 v4, v4, 6, v0
	ds_add_u32 v4, v205 offset:16384
.Lsel_skip_83:
	v_lshrrev_b32_e32 v5, s17, v98
	v_cmp_eq_u32_e32 vcc, v5, v2
	s_cbranch_vccz .Lsel_skip_84
	v_bfe_u32 v4, v98, s16, 8
	v_cndmask_b32_e32 v4, v41, v4, vcc
	v_lshl_add_u32 v4, v4, 6, v0
	ds_add_u32 v4, v205 offset:16384
.Lsel_skip_84:
	v_lshrrev_b32_e32 v5, s17, v97
	v_cmp_eq_u32_e32 vcc, v5, v2
	s_cbranch_vccz .Lsel_skip_85
	v_bfe_u32 v4, v97, s16, 8
	v_cndmask_b32_e32 v4, v41, v4, vcc
	v_lshl_add_u32 v4, v4, 6, v0
	ds_add_u32 v4, v205 offset:16384
.Lsel_skip_85:
	v_lshrrev_b32_e32 v5, s17, v100
	v_cmp_eq_u32_e32 vcc, v5, v2
	s_cbranch_vccz .Lsel_skip_86
	v_bfe_u32 v4, v100, s16, 8
	v_cndmask_b32_e32 v4, v41, v4, vcc
	v_lshl_add_u32 v4, v4, 6, v0
	ds_add_u32 v4, v205 offset:16384
.Lsel_skip_86:
	v_lshrrev_b32_e32 v5, s17, v99
	v_cmp_eq_u32_e32 vcc, v5, v2
	s_cbranch_vccz .Lsel_skip_87
	v_bfe_u32 v4, v99, s16, 8
	v_cndmask_b32_e32 v4, v41, v4, vcc
	v_lshl_add_u32 v4, v4, 6, v0
	ds_add_u32 v4, v205 offset:16384
.Lsel_skip_87:
	v_lshrrev_b32_e32 v5, s17, v102
	v_cmp_eq_u32_e32 vcc, v5, v2
	s_cbranch_vccz .Lsel_skip_88
	v_bfe_u32 v4, v102, s16, 8
	v_cndmask_b32_e32 v4, v41, v4, vcc
	v_lshl_add_u32 v4, v4, 6, v0
	ds_add_u32 v4, v205 offset:16384
.Lsel_skip_88:
	v_lshrrev_b32_e32 v5, s17, v101
	v_cmp_eq_u32_e32 vcc, v5, v2
	s_cbranch_vccz .Lsel_skip_89
	v_bfe_u32 v4, v101, s16, 8
	v_cndmask_b32_e32 v4, v41, v4, vcc
	v_lshl_add_u32 v4, v4, 6, v0
	ds_add_u32 v4, v205 offset:16384
.Lsel_skip_89:
	v_lshrrev_b32_e32 v5, s17, v104
	v_cmp_eq_u32_e32 vcc, v5, v2
	s_cbranch_vccz .Lsel_skip_90
	v_bfe_u32 v4, v104, s16, 8
	v_cndmask_b32_e32 v4, v41, v4, vcc
	v_lshl_add_u32 v4, v4, 6, v0
	ds_add_u32 v4, v205 offset:16384
.Lsel_skip_90:
	v_lshrrev_b32_e32 v5, s17, v103
	v_cmp_eq_u32_e32 vcc, v5, v2
	s_cbranch_vccz .Lsel_skip_91
	v_bfe_u32 v4, v103, s16, 8
	v_cndmask_b32_e32 v4, v41, v4, vcc
	v_lshl_add_u32 v4, v4, 6, v0
	ds_add_u32 v4, v205 offset:16384
.Lsel_skip_91:
	v_lshrrev_b32_e32 v5, s17, v106
	v_cmp_eq_u32_e32 vcc, v5, v2
	s_cbranch_vccz .Lsel_skip_92
	v_bfe_u32 v4, v106, s16, 8
	v_cndmask_b32_e32 v4, v41, v4, vcc
	v_lshl_add_u32 v4, v4, 6, v0
	ds_add_u32 v4, v205 offset:16384
.Lsel_skip_92:
	v_lshrrev_b32_e32 v5, s17, v105
	v_cmp_eq_u32_e32 vcc, v5, v2
	s_cbranch_vccz .Lsel_skip_93
	v_bfe_u32 v4, v105, s16, 8
	v_cndmask_b32_e32 v4, v41, v4, vcc
	v_lshl_add_u32 v4, v4, 6, v0
	ds_add_u32 v4, v205 offset:16384
.Lsel_skip_93:
	v_lshrrev_b32_e32 v5, s17, v108
	v_cmp_eq_u32_e32 vcc, v5, v2
	s_cbranch_vccz .Lsel_skip_94
	v_bfe_u32 v4, v108, s16, 8
	v_cndmask_b32_e32 v4, v41, v4, vcc
	v_lshl_add_u32 v4, v4, 6, v0
	ds_add_u32 v4, v205 offset:16384
.Lsel_skip_94:
	v_lshrrev_b32_e32 v5, s17, v107
	v_cmp_eq_u32_e32 vcc, v5, v2
	s_cbranch_vccz .Lsel_skip_95
	v_bfe_u32 v4, v107, s16, 8
	v_cndmask_b32_e32 v4, v41, v4, vcc
	v_lshl_add_u32 v4, v4, 6, v0
	ds_add_u32 v4, v205 offset:16384

; #define SEL_HADD(idx_) __hip_atomic_fetch_add(&hist[(idx_)], 1u, __ATOMIC_RELAXED, __HIP_MEMORY_SCOPE_WORKGROUP)
; __device__ __forceinline__ void sel_unit(LAS char* lds, int b, int u, const bf16_t* QI, const bf16_t* KIDX, const float* WIDX, unsigned long long* MASK) {
;     ...
;         for (int j = 0; j < 8; ++j) if (j < nj) {
; #pragma unroll
;             for (int kb = 0; kb < 4; ++kb)
; #pragma unroll
;                 for (int i = 0; i < 4; ++i) { const unsigned k = sc[j][kb][i] | zz; SEL_HADD((((k >> (shift + 8)) == pf) ? ((k >> shift) & 255u) * 16 : 4096u) + q16); __builtin_amdgcn_sched_barrier(0); }
.LBB0_744:
	v_lshrrev_b32_e32 v5, s17, v126
	s_waitcnt lgkmcnt(0)
	v_cmp_eq_u32_e32 vcc, v5, v2
	s_cbranch_vccz .Lsel_skip_96
	v_bfe_u32 v4, v126, s16, 8
	v_cndmask_b32_e32 v4, v41, v4, vcc
	v_lshl_add_u32 v4, v4, 6, v0
	ds_add_u32 v4, v205 offset:16384
.Lsel_skip_96:
	v_lshrrev_b32_e32 v5, s17, v125
	v_cmp_eq_u32_e32 vcc, v5, v2
	s_cbranch_vccz .Lsel_skip_97
	v_bfe_u32 v4, v125, s16, 8
	v_cndmask_b32_e32 v4, v41, v4, vcc
	v_lshl_add_u32 v4, v4, 6, v0
	ds_add_u32 v4, v205 offset:16384
.Lsel_skip_97:
	v_lshrrev_b32_e32 v5, s17, v128
	v_cmp_eq_u32_e32 vcc, v5, v2
	s_cbranch_vccz .Lsel_skip_98
	v_bfe_u32 v4, v128, s16, 8
	v_cndmask_b32_e32 v4, v41, v4, vcc
	v_lshl_add_u32 v4, v4, 6, v0
	ds_add_u32 v4, v205 offset:16384
.Lsel_skip_98:
	v_lshrrev_b32_e32 v5, s17, v127
	v_cmp_eq_u32_e32 vcc, v5, v2
	s_cbranch_vccz .Lsel_skip_99
	v_bfe_u32 v4, v127, s16, 8
	v_cndmask_b32_e32 v4, v41, v4, vcc
	v_lshl_add_u32 v4, v4, 6, v0
	ds_add_u32 v4, v205 offset:16384
.Lsel_skip_99:
	v_lshrrev_b32_e32 v5, s17, v130
	v_cmp_eq_u32_e32 vcc, v5, v2
	s_cbranch_vccz .Lsel_skip_100
	v_bfe_u32 v4, v130, s16, 8
	v_cndmask_b32_e32 v4, v41, v4, vcc
	v_lshl_add_u32 v4, v4, 6, v0
	ds_add_u32 v4, v205 offset:16384
.Lsel_skip_100:
	v_lshrrev_b32_e32 v5, s17, v129
	v_cmp_eq_u32_e32 vcc, v5, v2
	s_cbranch_vccz .Lsel_skip_101
	v_bfe_u32 v4, v129, s16, 8
	v_cndmask_b32_e32 v4, v41, v4, vcc
	v_lshl_add_u32 v4, v4, 6, v0
	ds_add_u32 v4, v205 offset:16384
.Lsel_skip_101:
	v_lshrrev_b32_e32 v5, s17, v132
	v_cmp_eq_u32_e32 vcc, v5, v2
	s_cbranch_vccz .Lsel_skip_102
	v_bfe_u32 v4, v132, s16, 8
	v_cndmask_b32_e32 v4, v41, v4, vcc
	v_lshl_add_u32 v4, v4, 6, v0
	ds_add_u32 v4, v205 offset:16384
.Lsel_skip_102:
	v_lshrrev_b32_e32 v5, s17, v131
	v_cmp_eq_u32_e32 vcc, v5, v2
	s_cbranch_vccz .Lsel_skip_103
	v_bfe_u32 v4, v131, s16, 8
	v_cndmask_b32_e32 v4, v41, v4, vcc
	v_lshl_add_u32 v4, v4, 6, v0
	ds_add_u32 v4, v205 offset:16384
.Lsel_skip_103:
	v_lshrrev_b32_e32 v5, s17, v134
	v_cmp_eq_u32_e32 vcc, v5, v2
	s_cbranch_vccz .Lsel_skip_104
	v_bfe_u32 v4, v134, s16, 8
	v_cndmask_b32_e32 v4, v41, v4, vcc
	v_lshl_add_u32 v4, v4, 6, v0
	ds_add_u32 v4, v205 offset:16384
.Lsel_skip_104:
	v_lshrrev_b32_e32 v5, s17, v133
	v_cmp_eq_u32_e32 vcc, v5, v2
	s_cbranch_vccz .Lsel_skip_105
	v_bfe_u32 v4, v133, s16, 8
	v_cndmask_b32_e32 v4, v41, v4, vcc
	v_lshl_add_u32 v4, v4, 6, v0
	ds_add_u32 v4, v205 offset:16384
.Lsel_skip_105:
	v_lshrrev_b32_e32 v5, s17, v136
	v_cmp_eq_u32_e32 vcc, v5, v2
	s_cbranch_vccz .Lsel_skip_106
	v_bfe_u32 v4, v136, s16, 8
	v_cndmask_b32_e32 v4, v41, v4, vcc
	v_lshl_add_u32 v4, v4, 6, v0
	ds_add_u32 v4, v205 offset:16384
.Lsel_skip_106:
	v_lshrrev_b32_e32 v5, s17, v135
	v_cmp_eq_u32_e32 vcc, v5, v2
	s_cbranch_vccz .Lsel_skip_107
	v_bfe_u32 v4, v135, s16, 8
	v_cndmask_b32_e32 v4, v41, v4, vcc
	v_lshl_add_u32 v4, v4, 6, v0
	ds_add_u32 v4, v205 offset:16384
.Lsel_skip_107:
	v_lshrrev_b32_e32 v5, s17, v139
	v_cmp_eq_u32_e32 vcc, v5, v2
	s_cbranch_vccz .Lsel_skip_108
	v_bfe_u32 v4, v139, s16, 8
	v_cndmask_b32_e32 v4, v41, v4, vcc
	v_lshl_add_u32 v4, v4, 6, v0
	ds_add_u32 v4, v205 offset:16384
.Lsel_skip_108:
	v_lshrrev_b32_e32 v5, s17, v138
	v_cmp_eq_u32_e32 vcc, v5, v2
	s_cbranch_vccz .Lsel_skip_109
	v_bfe_u32 v4, v138, s16, 8
	v_cndmask_b32_e32 v4, v41, v4, vcc
	v_lshl_add_u32 v4, v4, 6, v0
	ds_add_u32 v4, v205 offset:16384
.Lsel_skip_109:
	v_lshrrev_b32_e32 v5, s17, v141
	v_cmp_eq_u32_e32 vcc, v5, v2
	s_cbranch_vccz .Lsel_skip_110
	v_bfe_u32 v4, v141, s16, 8
	v_cndmask_b32_e32 v4, v41, v4, vcc
	v_lshl_add_u32 v4, v4, 6, v0
	ds_add_u32 v4, v205 offset:16384
.Lsel_skip_110:
	v_lshrrev_b32_e32 v5, s17, v140
	v_cmp_eq_u32_e32 vcc, v5, v2
	s_cbranch_vccz .Lsel_skip_111
	v_bfe_u32 v4, v140, s16, 8
	v_cndmask_b32_e32 v4, v41, v4, vcc
	v_lshl_add_u32 v4, v4, 6, v0
	ds_add_u32 v4, v205 offset:16384

; #define SEL_HADD(idx_) __hip_atomic_fetch_add(&hist[(idx_)], 1u, __ATOMIC_RELAXED, __HIP_MEMORY_SCOPE_WORKGROUP)
; __device__ __forceinline__ void sel_unit(LAS char* lds, int b, int u, const bf16_t* QI, const bf16_t* KIDX, const float* WIDX, unsigned long long* MASK) {
;     ...
;         for (int j = 0; j < 8; ++j) if (j < nj) {
; #pragma unroll
;             for (int kb = 0; kb < 4; ++kb)
; #pragma unroll
;                 for (int i = 0; i < 4; ++i) { const unsigned k = sc[j][kb][i] | zz; SEL_HADD((((k >> (shift + 8)) == pf) ? ((k >> shift) & 255u) * 16 : 4096u) + q16); __builtin_amdgcn_sched_barrier(0); }
.LBB0_746:
	v_lshrrev_b32_e32 v5, s17, v192
	s_waitcnt lgkmcnt(0)
	v_cmp_eq_u32_e32 vcc, v5, v2
	s_cbranch_vccz .Lsel_skip_112
	v_bfe_u32 v4, v192, s16, 8
	v_cndmask_b32_e32 v4, v41, v4, vcc
	v_lshl_add_u32 v4, v4, 6, v0
	ds_add_u32 v4, v205 offset:16384
.Lsel_skip_112:
	v_lshrrev_b32_e32 v5, s17, v191
	v_cmp_eq_u32_e32 vcc, v5, v2
	s_cbranch_vccz .Lsel_skip_113
	v_bfe_u32 v4, v191, s16, 8
	v_cndmask_b32_e32 v4, v41, v4, vcc
	v_lshl_add_u32 v4, v4, 6, v0
	ds_add_u32 v4, v205 offset:16384
.Lsel_skip_113:
	v_lshrrev_b32_e32 v5, s17, v194
	v_cmp_eq_u32_e32 vcc, v5, v2
	s_cbranch_vccz .Lsel_skip_114
	v_bfe_u32 v4, v194, s16, 8
	v_cndmask_b32_e32 v4, v41, v4, vcc
	v_lshl_add_u32 v4, v4, 6, v0
	ds_add_u32 v4, v205 offset:16384
.Lsel_skip_114:
	v_lshrrev_b32_e32 v5, s17, v193
	v_cmp_eq_u32_e32 vcc, v5, v2
	s_cbranch_vccz .Lsel_skip_115
	v_bfe_u32 v4, v193, s16, 8
	v_cndmask_b32_e32 v4, v41, v4, vcc
	v_lshl_add_u32 v4, v4, 6, v0
	ds_add_u32 v4, v205 offset:16384
.Lsel_skip_115:
	v_lshrrev_b32_e32 v5, s17, v196
	v_cmp_eq_u32_e32 vcc, v5, v2
	s_cbranch_vccz .Lsel_skip_116
	v_bfe_u32 v4, v196, s16, 8
	v_cndmask_b32_e32 v4, v41, v4, vcc
	v_lshl_add_u32 v4, v4, 6, v0
	ds_add_u32 v4, v205 offset:16384
.Lsel_skip_116:
	v_lshrrev_b32_e32 v5, s17, v195
	v_cmp_eq_u32_e32 vcc, v5, v2
	s_cbranch_vccz .Lsel_skip_117
	v_bfe_u32 v4, v195, s16, 8
	v_cndmask_b32_e32 v4, v41, v4, vcc
	v_lshl_add_u32 v4, v4, 6, v0
	ds_add_u32 v4, v205 offset:16384
.Lsel_skip_117:
	v_lshrrev_b32_e32 v5, s17, v198
	v_cmp_eq_u32_e32 vcc, v5, v2
	s_cbranch_vccz .Lsel_skip_118
	v_bfe_u32 v4, v198, s16, 8
	v_cndmask_b32_e32 v4, v41, v4, vcc
	v_lshl_add_u32 v4, v4, 6, v0
	ds_add_u32 v4, v205 offset:16384
.Lsel_skip_118:
	v_lshrrev_b32_e32 v5, s17, v197
	v_cmp_eq_u32_e32 vcc, v5, v2
	s_cbranch_vccz .Lsel_skip_119
	v_bfe_u32 v4, v197, s16, 8
	v_cndmask_b32_e32 v4, v41, v4, vcc
	v_lshl_add_u32 v4, v4, 6, v0
	ds_add_u32 v4, v205 offset:16384
.Lsel_skip_119:
	v_lshrrev_b32_e32 v5, s17, v57
	v_cmp_eq_u32_e32 vcc, v5, v2
	s_cbranch_vccz .Lsel_skip_120
	v_bfe_u32 v4, v57, s16, 8
	v_cndmask_b32_e32 v4, v41, v4, vcc
	v_lshl_add_u32 v4, v4, 6, v0
	ds_add_u32 v4, v205 offset:16384
.Lsel_skip_120:
	v_lshrrev_b32_e32 v5, s17, v56
	v_cmp_eq_u32_e32 vcc, v5, v2
	s_cbranch_vccz .Lsel_skip_121
	v_bfe_u32 v4, v56, s16, 8
	v_cndmask_b32_e32 v4, v41, v4, vcc
	v_lshl_add_u32 v4, v4, 6, v0
	ds_add_u32 v4, v205 offset:16384
.Lsel_skip_121:
	v_lshrrev_b32_e32 v5, s17, v55
	v_cmp_eq_u32_e32 vcc, v5, v2
	s_cbranch_vccz .Lsel_skip_122
	v_bfe_u32 v4, v55, s16, 8
	v_cndmask_b32_e32 v4, v41, v4, vcc
	v_lshl_add_u32 v4, v4, 6, v0
	ds_add_u32 v4, v205 offset:16384
.Lsel_skip_122:
	v_lshrrev_b32_e32 v5, s17, v54
	v_cmp_eq_u32_e32 vcc, v5, v2
	s_cbranch_vccz .Lsel_skip_123
	v_bfe_u32 v4, v54, s16, 8
	v_cndmask_b32_e32 v4, v41, v4, vcc
	v_lshl_add_u32 v4, v4, 6, v0
	ds_add_u32 v4, v205 offset:16384
.Lsel_skip_123:
	v_lshrrev_b32_e32 v5, s17, v218
	v_cmp_eq_u32_e32 vcc, v5, v2
	s_cbranch_vccz .Lsel_skip_124
	v_bfe_u32 v4, v218, s16, 8
	v_cndmask_b32_e32 v4, v41, v4, vcc
	v_lshl_add_u32 v4, v4, 6, v0
	ds_add_u32 v4, v205 offset:16384
.Lsel_skip_124:
	v_lshrrev_b32_e32 v5, s17, v199
	v_cmp_eq_u32_e32 vcc, v5, v2
	s_cbranch_vccz .Lsel_skip_125
	v_bfe_u32 v4, v199, s16, 8
	v_cndmask_b32_e32 v4, v41, v4, vcc
	v_lshl_add_u32 v4, v4, 6, v0
	ds_add_u32 v4, v205 offset:16384
.Lsel_skip_125:
	v_lshrrev_b32_e32 v5, s17, v220
	v_cmp_eq_u32_e32 vcc, v5, v2
	s_cbranch_vccz .Lsel_skip_126
	v_bfe_u32 v4, v220, s16, 8
	v_cndmask_b32_e32 v4, v41, v4, vcc
	v_lshl_add_u32 v4, v4, 6, v0
	ds_add_u32 v4, v205 offset:16384
.Lsel_skip_126:
	v_lshrrev_b32_e32 v5, s17, v219
	v_cmp_eq_u32_e32 vcc, v5, v2
	s_cbranch_vccz .Lsel_skip_127
	v_bfe_u32 v4, v219, s16, 8
	v_cndmask_b32_e32 v4, v41, v4, vcc
	v_lshl_add_u32 v4, v4, 6, v0
	ds_add_u32 v4, v205 offset:16384
